# out-proj epilogue: 32 serial load-wait-fma-store round trips replaced by a 16-deep pipelined sequence with counted vmcnt
# baseline (speedup 1.0000x reference)
;     __device__ __forceinline__ void operator()(const f32x4 (&acc)[2][2][4][2], const Unit& u, int wr, int wc, int fr, int fq) const {
;     ...
;         const int row0 = u.pm * BM + wr * 64 + fr, col0 = u.pn * BM + wc * 32 + 8 * fq;
;         f32x4 g[2][2];
; #pragma unroll
;         for (int bj = 0; bj < 2; ++bj)
; #pragma unroll
;             for (int n = 0; n < 2; ++n) g[bj][n] = *(const f32x4*)(gate + col0 + bj * HALF + 4 * n);
; #pragma unroll
;         for (int ai = 0; ai < 2; ++ai)
; #pragma unroll
;             for (int m = 0; m < 4; ++m) { const size_t ro = (size_t)(row0 + ai * HALF + m * 16) * DMODEL + col0;
; #pragma unroll
;                 for (int bj = 0; bj < 2; ++bj)
; #pragma unroll
;                     for (int n = 0; n < 2; ++n) { const f32x4 x = *(const f32x4*)(xin + ro + bj * HALF + 4 * n); *(f32x4*)(xout + ro + bj * HALF + 4 * n) = x + g[bj][n] * acc[ai][bj][m][n]; } }
.LBB0_809:
	v_mov_b32_e32 v160, v156
	v_mov_b32_e32 v124, v157
	s_lshl_b32 s15, s22, 8
	s_add_i32 s15, s15, s41
	s_lshl_b32 s22, s23, 8
	s_or_b32 s22, s22, s42
	v_add_u32_e32 v160, s15, v160
	v_lshl_add_u32 v154, v124, 3, s22
	v_ashrrev_i32_e32 v161, 31, v160
	v_ashrrev_i32_e32 v155, 31, v154
	v_lshlrev_b64 v[160:161], 11, v[160:161]
	v_lshl_add_u64 v[132:133], v[154:155], 2, s[10:11]
	v_lshl_add_u64 v[154:155], v[160:161], 0, v[154:155]
	v_lshlrev_b64 v[154:155], 2, v[154:155]
	v_lshl_add_u64 v[164:165], s[8:9], 0, v[154:155]
	global_load_dwordx4 v[136:139], v[132:133], off offset:16
	global_load_dwordx4 v[140:143], v[132:133], off
	global_load_dwordx4 v[124:127], v[132:133], off offset:528
	s_nop 0
	global_load_dwordx4 v[132:135], v[132:133], off offset:512
	s_andn2_b64 vcc, exec, s[20:21]
	v_add_u32_e32 v161, 0x20000, v154
	v_add_u32_e32 v162, 0x40000, v154
	v_add_u32_e32 v163, 0x60000, v154
	v_add_u32_e32 v164, 0x100000, v154
	v_add_u32_e32 v165, 0x120000, v154
	v_add_u32_e32 v166, 0x140000, v154
	v_add_u32_e32 v167, 0x160000, v154
	global_load_dwordx4 v[168:171], v154, s[8:9]
	global_load_dwordx4 v[172:175], v154, s[8:9] offset:16
	global_load_dwordx4 v[176:179], v154, s[8:9] offset:512
	global_load_dwordx4 v[180:183], v154, s[8:9] offset:528
	global_load_dwordx4 v[184:187], v161, s[8:9]
	global_load_dwordx4 v[190:193], v161, s[8:9] offset:16
	global_load_dwordx4 v[194:197], v161, s[8:9] offset:512
	global_load_dwordx4 v[198:201], v161, s[8:9] offset:528
	global_load_dwordx4 v[202:205], v162, s[8:9]
	global_load_dwordx4 v[206:209], v162, s[8:9] offset:16
	global_load_dwordx4 v[218:221], v162, s[8:9] offset:512
	global_load_dwordx4 v[222:225], v162, s[8:9] offset:528
	global_load_dwordx4 v[226:229], v163, s[8:9]
	global_load_dwordx4 v[234:237], v163, s[8:9] offset:16
	global_load_dwordx4 v[238:241], v163, s[8:9] offset:512
	global_load_dwordx4 v[242:245], v163, s[8:9] offset:528
	s_waitcnt vmcnt(15)
	v_pk_fma_f32 v[130:131], v[130:131], v[142:143], v[170:171]
	v_pk_fma_f32 v[128:129], v[128:129], v[140:141], v[168:169]
	global_store_dwordx4 v154, v[128:131], s[6:7]
	global_load_dwordx4 v[168:171], v164, s[8:9]
	s_waitcnt vmcnt(16)
	v_pk_fma_f32 v[122:123], v[122:123], v[138:139], v[174:175]
	v_pk_fma_f32 v[120:121], v[120:121], v[136:137], v[172:173]
	global_store_dwordx4 v154, v[120:123], s[6:7] offset:16
	global_load_dwordx4 v[172:175], v164, s[8:9] offset:16
	s_waitcnt vmcnt(17)
	v_pk_fma_f32 v[118:119], v[118:119], v[134:135], v[178:179]
	v_pk_fma_f32 v[116:117], v[116:117], v[132:133], v[176:177]
	global_store_dwordx4 v154, v[116:119], s[6:7] offset:512
	global_load_dwordx4 v[176:179], v164, s[8:9] offset:512
	s_waitcnt vmcnt(18)
	v_pk_fma_f32 v[114:115], v[114:115], v[126:127], v[182:183]
	v_pk_fma_f32 v[112:113], v[112:113], v[124:125], v[180:181]
	global_store_dwordx4 v154, v[112:115], s[6:7] offset:528
	global_load_dwordx4 v[180:183], v164, s[8:9] offset:528
	s_waitcnt vmcnt(19)
	v_pk_fma_f32 v[110:111], v[110:111], v[142:143], v[186:187]
	v_pk_fma_f32 v[108:109], v[108:109], v[140:141], v[184:185]
	global_store_dwordx4 v161, v[108:111], s[6:7]
	global_load_dwordx4 v[184:187], v165, s[8:9]
	s_waitcnt vmcnt(20)
	v_pk_fma_f32 v[106:107], v[106:107], v[138:139], v[192:193]
	v_pk_fma_f32 v[104:105], v[104:105], v[136:137], v[190:191]
	global_store_dwordx4 v161, v[104:107], s[6:7] offset:16
	global_load_dwordx4 v[190:193], v165, s[8:9] offset:16
	s_waitcnt vmcnt(21)
	v_pk_fma_f32 v[102:103], v[102:103], v[134:135], v[196:197]
	v_pk_fma_f32 v[100:101], v[100:101], v[132:133], v[194:195]
	global_store_dwordx4 v161, v[100:103], s[6:7] offset:512
	global_load_dwordx4 v[194:197], v165, s[8:9] offset:512
	s_waitcnt vmcnt(22)
	v_pk_fma_f32 v[98:99], v[98:99], v[126:127], v[200:201]
	v_pk_fma_f32 v[96:97], v[96:97], v[124:125], v[198:199]
	global_store_dwordx4 v161, v[96:99], s[6:7] offset:528
	global_load_dwordx4 v[198:201], v165, s[8:9] offset:528
	s_waitcnt vmcnt(23)
	v_pk_fma_f32 v[94:95], v[94:95], v[142:143], v[204:205]
	v_pk_fma_f32 v[92:93], v[92:93], v[140:141], v[202:203]
	global_store_dwordx4 v162, v[92:95], s[6:7]
	global_load_dwordx4 v[202:205], v166, s[8:9]
	s_waitcnt vmcnt(24)
	v_pk_fma_f32 v[90:91], v[90:91], v[138:139], v[208:209]
	v_pk_fma_f32 v[88:89], v[88:89], v[136:137], v[206:207]
	global_store_dwordx4 v162, v[88:91], s[6:7] offset:16
	global_load_dwordx4 v[206:209], v166, s[8:9] offset:16
	s_waitcnt vmcnt(25)
;     __device__ __forceinline__ void operator()(const f32x4 (&acc)[2][2][4][2], const Unit& u, int wr, int wc, int fr, int fq) const {
;     ...
;         for (int ai = 0; ai < 2; ++ai)
; #pragma unroll
;             for (int m = 0; m < 4; ++m) { const size_t ro = (size_t)(row0 + ai * HALF + m * 16) * DMODEL + col0;
; #pragma unroll
;                 for (int bj = 0; bj < 2; ++bj)
; #pragma unroll
;                     for (int n = 0; n < 2; ++n) { const f32x4 x = *(const f32x4*)(xin + ro + bj * HALF + 4 * n); *(f32x4*)(xout + ro + bj * HALF + 4 * n) = x + g[bj][n] * acc[ai][bj][m][n]; } }
	v_pk_fma_f32 v[86:87], v[86:87], v[134:135], v[220:221]
	v_pk_fma_f32 v[84:85], v[84:85], v[132:133], v[218:219]
	global_store_dwordx4 v162, v[84:87], s[6:7] offset:512
	global_load_dwordx4 v[218:221], v166, s[8:9] offset:512
	s_waitcnt vmcnt(26)
	v_pk_fma_f32 v[82:83], v[82:83], v[126:127], v[224:225]
	v_pk_fma_f32 v[80:81], v[80:81], v[124:125], v[222:223]
	global_store_dwordx4 v162, v[80:83], s[6:7] offset:528
	global_load_dwordx4 v[222:225], v166, s[8:9] offset:528
	s_waitcnt vmcnt(27)
	v_pk_fma_f32 v[78:79], v[78:79], v[142:143], v[228:229]
	v_pk_fma_f32 v[76:77], v[76:77], v[140:141], v[226:227]
	global_store_dwordx4 v163, v[76:79], s[6:7]
	global_load_dwordx4 v[226:229], v167, s[8:9]
	s_waitcnt vmcnt(28)
	v_pk_fma_f32 v[74:75], v[74:75], v[138:139], v[236:237]
	v_pk_fma_f32 v[72:73], v[72:73], v[136:137], v[234:235]
	global_store_dwordx4 v163, v[72:75], s[6:7] offset:16
	global_load_dwordx4 v[234:237], v167, s[8:9] offset:16
	s_waitcnt vmcnt(29)
	v_pk_fma_f32 v[70:71], v[70:71], v[134:135], v[240:241]
	v_pk_fma_f32 v[68:69], v[68:69], v[132:133], v[238:239]
	global_store_dwordx4 v163, v[68:71], s[6:7] offset:512
	global_load_dwordx4 v[238:241], v167, s[8:9] offset:512
	s_waitcnt vmcnt(30)
	v_pk_fma_f32 v[66:67], v[66:67], v[126:127], v[244:245]
	v_pk_fma_f32 v[64:65], v[64:65], v[124:125], v[242:243]
	global_store_dwordx4 v163, v[64:67], s[6:7] offset:528
	global_load_dwordx4 v[242:245], v167, s[8:9] offset:528
	s_waitcnt vmcnt(30)
	v_pk_fma_f32 v[62:63], v[62:63], v[142:143], v[170:171]
	v_pk_fma_f32 v[60:61], v[60:61], v[140:141], v[168:169]
	global_store_dwordx4 v164, v[60:63], s[6:7]
	s_waitcnt vmcnt(29)
	v_pk_fma_f32 v[58:59], v[58:59], v[138:139], v[174:175]
	v_pk_fma_f32 v[56:57], v[56:57], v[136:137], v[172:173]
	global_store_dwordx4 v164, v[56:59], s[6:7] offset:16
	s_waitcnt vmcnt(28)
	v_pk_fma_f32 v[54:55], v[54:55], v[134:135], v[178:179]
	v_pk_fma_f32 v[52:53], v[52:53], v[132:133], v[176:177]
	global_store_dwordx4 v164, v[52:55], s[6:7] offset:512
	s_waitcnt vmcnt(27)
	v_pk_fma_f32 v[50:51], v[50:51], v[126:127], v[182:183]
	v_pk_fma_f32 v[48:49], v[48:49], v[124:125], v[180:181]
	global_store_dwordx4 v164, v[48:51], s[6:7] offset:528
	s_waitcnt vmcnt(26)
	v_pk_fma_f32 v[46:47], v[46:47], v[142:143], v[186:187]
	v_pk_fma_f32 v[44:45], v[44:45], v[140:141], v[184:185]
	global_store_dwordx4 v165, v[44:47], s[6:7]
	s_waitcnt vmcnt(25)
	v_pk_fma_f32 v[42:43], v[42:43], v[138:139], v[192:193]
	v_pk_fma_f32 v[40:41], v[40:41], v[136:137], v[190:191]
	global_store_dwordx4 v165, v[40:43], s[6:7] offset:16
	s_waitcnt vmcnt(24)
	v_pk_fma_f32 v[38:39], v[38:39], v[134:135], v[196:197]
	v_pk_fma_f32 v[36:37], v[36:37], v[132:133], v[194:195]
	global_store_dwordx4 v165, v[36:39], s[6:7] offset:512
	s_waitcnt vmcnt(23)
	v_pk_fma_f32 v[34:35], v[34:35], v[126:127], v[200:201]
	v_pk_fma_f32 v[32:33], v[32:33], v[124:125], v[198:199]
	global_store_dwordx4 v165, v[32:35], s[6:7] offset:528
	s_waitcnt vmcnt(22)
	v_pk_fma_f32 v[30:31], v[30:31], v[142:143], v[204:205]
	v_pk_fma_f32 v[28:29], v[28:29], v[140:141], v[202:203]
	global_store_dwordx4 v166, v[28:31], s[6:7]
	s_waitcnt vmcnt(21)
	v_pk_fma_f32 v[26:27], v[26:27], v[138:139], v[208:209]
	v_pk_fma_f32 v[24:25], v[24:25], v[136:137], v[206:207]
	global_store_dwordx4 v166, v[24:27], s[6:7] offset:16
	s_waitcnt vmcnt(20)
	v_pk_fma_f32 v[22:23], v[22:23], v[134:135], v[220:221]
	v_pk_fma_f32 v[20:21], v[20:21], v[132:133], v[218:219]
	global_store_dwordx4 v166, v[20:23], s[6:7] offset:512
	s_waitcnt vmcnt(19)
	v_pk_fma_f32 v[18:19], v[18:19], v[126:127], v[224:225]
	v_pk_fma_f32 v[16:17], v[16:17], v[124:125], v[222:223]
	global_store_dwordx4 v166, v[16:19], s[6:7] offset:528
	s_waitcnt vmcnt(18)
	v_pk_fma_f32 v[14:15], v[14:15], v[142:143], v[228:229]
	v_pk_fma_f32 v[12:13], v[12:13], v[140:141], v[226:227]
	global_store_dwordx4 v167, v[12:15], s[6:7]
	s_waitcnt vmcnt(17)
	v_pk_fma_f32 v[10:11], v[10:11], v[138:139], v[236:237]
	v_pk_fma_f32 v[8:9], v[8:9], v[136:137], v[234:235]
	global_store_dwordx4 v167, v[8:11], s[6:7] offset:16
	s_waitcnt vmcnt(16)
	v_pk_fma_f32 v[6:7], v[6:7], v[134:135], v[240:241]
	v_pk_fma_f32 v[4:5], v[4:5], v[132:133], v[238:239]
	global_store_dwordx4 v167, v[4:7], s[6:7] offset:512
	s_waitcnt vmcnt(15)
	v_pk_fma_f32 v[2:3], v[2:3], v[126:127], v[244:245]
	v_pk_fma_f32 v[0:1], v[0:1], v[124:125], v[242:243]
	global_store_dwordx4 v167, v[0:3], s[6:7] offset:528
	s_mov_b64 s[22:23], -1
	s_cbranch_vccnz .LBB0_802
	s_andn2_b64 vcc, exec, s[4:5]
	s_cbranch_vccnz .LBB0_801
	s_barrier
	s_branch .LBB0_801
